# gated-DeltaNet: next chunk's K/Q fragments fetched right after the solve instead of at the loop top
# baseline (speedup 1.0000x reference)
; __device__ __forceinline__ int otid() { int t = threadIdx.x; asm volatile("" : "+v"(t)); return t; }
; __device__ __forceinline__ void gdn_item(const Params& p, int item, float* sm) {
;   const int b = item >> 5, h = (item >> 3) & 3, c0 = (item & 7) * 16;
;   const bf16_t* gp = (const bf16_t*)p.out;
;   const float* gg = (const float*)(p.ws + OFF_GG);
;   bf16_t* O = (bf16_t*)(p.ws + OFF_O);
;   constexpr int TC = 16;
;   constexpr int BUF = 2 * TC * 128 + TC * 16 + 2 * TC + TC * 16 + TC;
;   const int tid = otid(), lane = tid & 63, wave = tid >> 6;
;   const int sub = lane & 15, cw = wave * 4 + (lane >> 4);
;   const int ltt = tid >> 4, lseg = tid & 15;
;   float S[8];
; #pragma unroll
;   for (int i = 0; i < 8; i++) S[i] = 0.f;
;   const size_t rowb = (size_t)b * LP;
;   uint4 pq, pk; bf16_t pv; float pg = 0.f, pb = 0.f;
;     ...
;   __syncthreads();
;   GDN_LOAD(PADR)
;   GDN_STORE(0)
;   __syncthreads();
.Lgd_item:
	s_setprio 3
	v_readlane_b32 s14, v244, 27
	v_readlane_b32 s8, v247, 3
	v_readlane_b32 s9, v247, 4
	v_readlane_b32 s4, v247, 1
	v_readlane_b32 s5, v247, 2
	v_and_b32_e32 v136, 15, v2
	v_lshrrev_b32_e32 v137, 4, v2
	v_bfe_u32 v138, v2, 4, 2
	v_lshrrev_b32_e32 v139, 6, v2
	s_lshr_b32 s10, s14, 5
	s_bfe_u32 s11, s14, 0x20003
	s_and_b32 s12, s14, 7
	s_lshl_b32 s12, s12, 5
	s_mul_i32 s13, s10, 0x2080
	s_add_i32 s13, s13, 0x70
	s_add_u32 s6, s8, 0x19c8c000
	s_addc_u32 s7, s9, 0
	s_add_u32 s8, s8, 0x19d90000
	s_addc_u32 s9, s9, 0
	s_lshl_b32 s14, s10, 2
	s_add_i32 s14, s14, s11
	s_mul_i32 s14, s14, 0x80400
	s_add_u32 s10, s4, 0x71a0000
	s_addc_u32 s15, s5, 0
	s_add_u32 s10, s10, s14
	s_addc_u32 s11, s15, 0
	v_readfirstlane_b32 s100, v139
	v_lshlrev_b32_e32 v151, 9, v136
	v_lshl_add_u32 v151, v139, 7, v151
	v_lshl_add_u32 v151, v138, 4, v151
	v_lshlrev_b32_e32 v152, 11, v138
	v_lshl_add_u32 v152, v139, 7, v152
	v_lshl_add_u32 v152, v136, 2, v152
	v_lshlrev_b32_e32 v153, 6, v136
	v_lshl_add_u32 v153, v138, 4, v153
	v_lshlrev_b32_e32 v154, 4, v138
	v_and_b32_e32 v140, 63, v2
	v_lshlrev_b32_e32 v156, 4, v140
	v_add_u32_e32 v156, 0x8a00, v156
	s_mul_i32 s101, s100, 0xc00
	v_add_u32_e32 v155, s101, v156
	v_lshlrev_b32_e32 v157, 5, v2
	v_lshl_add_u32 v158, v136, 4, v137
	v_lshlrev_b32_e32 v158, 2, v158
	v_add_u32_e32 v158, 16384, v158
	v_lshlrev_b32_e32 v159, 2, v136
	v_lshlrev_b32_e32 v141, 2, v138
	v_add_u32_e32 v142, 0, v141
	v_cmp_le_u32_e32 vcc, v142, v136
	s_nop 1
	v_cndmask_b32_e64 v166, 0, 1.0, vcc
	v_add_u32_e32 v142, 1, v141
	v_cmp_le_u32_e32 vcc, v142, v136
	s_nop 1
	v_cndmask_b32_e64 v167, 0, 1.0, vcc
	v_add_u32_e32 v142, 2, v141
	v_cmp_le_u32_e32 vcc, v142, v136
	s_nop 1
	v_cndmask_b32_e64 v168, 0, 1.0, vcc
	v_add_u32_e32 v142, 3, v141
	v_cmp_le_u32_e32 vcc, v142, v136
	s_nop 1
	v_cndmask_b32_e64 v169, 0, 1.0, vcc
	v_readlane_b32 s101, v244, 27
	s_bfe_u32 s101, s101, 0x20003
	v_add_u32_e32 v142, s13, v137
	s_lshl_b32 s14, s101, 8
	v_lshl_add_u32 v143, v136, 4, s14
	s_movk_i32 s15, 0xc00
	v_mad_u32_u24 v118, v142, s15, v143
	s_add_i32 s14, s14, s12
	v_lshl_add_u32 v143, v136, 1, s14
	v_mad_u32_u24 v119, v142, s15, v143
	v_add_u32_e32 v119, 0x800, v119
	v_add_u32_e32 v142, s13, v136
	s_lshl_b32 s15, s101, 2
	v_lshl_add_u32 v140, v142, 5, s15
	v_add_u32_e32 v142, s13, v141
	v_lshl_add_u32 v57, v142, 11, v143
	v_add_u32_e32 v57, 0x400, v57
	v_add_u32_e32 v58, 0x1000, v57
	v_lshlrev_b32_e32 v59, 6, v136
	v_lshl_add_u32 v59, v138, 4, v59
	v_readlane_b32 s14, v244, 27
	s_lshr_b32 s14, s14, 3
	s_mul_i32 s12, s14, 0x80400
	v_readlane_b32 s14, v247, 3
	v_readlane_b32 s15, v247, 4
	s_add_u32 s14, s14, 0xac40000
	s_addc_u32 s15, s15, 0
	s_add_u32 s14, s14, s12
	s_addc_u32 s15, s15, 0
	v_mov_b32_e32 v12, 0
	v_mov_b32_e32 v13, 0
	v_mov_b32_e32 v14, 0
	v_mov_b32_e32 v15, 0
	v_mov_b32_e32 v16, 0
	v_mov_b32_e32 v17, 0
	v_mov_b32_e32 v18, 0
	v_mov_b32_e32 v19, 0
	s_barrier
	global_load_dwordx4 v[108:111], v118, s[4:5]
	global_load_dwordx4 v[112:115], v118, s[4:5] offset:1024
	global_load_ushort v116, v119, s[4:5]
	global_load_dword v117, v140, s[6:7]
	s_add_u32 s4, s4, 0xc000
	s_addc_u32 s5, s5, 0
	s_add_u32 s6, s6, 0x200
	s_addc_u32 s7, s7, 0
	global_load_dwordx4 v[88:91], v59, s[10:11]
	s_add_u32 s10, s10, 0x400
	s_addc_u32 s11, s11, 0
	global_load_dwordx4 v[92:95], v59, s[14:15]
	s_add_u32 s14, s14, 0x400
	s_addc_u32 s15, s15, 0
	v_mov_b32_e32 v148, v157
	v_mov_b32_e32 v149, v158
	v_mov_b32_e32 v150, v159
	s_waitcnt vmcnt(0)
	v_lshlrev_b32_e32 v120, 16, v108
	v_and_b32_e32 v121, 0xffff0000, v108
	v_lshlrev_b32_e32 v122, 16, v109
	v_and_b32_e32 v123, 0xffff0000, v109
	v_lshlrev_b32_e32 v124, 16, v110
	v_and_b32_e32 v125, 0xffff0000, v110
	v_lshlrev_b32_e32 v126, 16, v111
	v_and_b32_e32 v127, 0xffff0000, v111
	v_lshlrev_b32_e32 v128, 16, v112
	v_and_b32_e32 v129, 0xffff0000, v112
	v_lshlrev_b32_e32 v130, 16, v113
	v_and_b32_e32 v131, 0xffff0000, v113
	v_lshlrev_b32_e32 v132, 16, v114
	v_and_b32_e32 v133, 0xffff0000, v114
	v_lshlrev_b32_e32 v134, 16, v115
	v_and_b32_e32 v135, 0xffff0000, v115
	v_mov_b32_e32 v136, v117
	v_lshlrev_b32_e32 v137, 16, v116
	s_nop 0
	v_add_f32_dpp v136, v136, v136 row_shr:1 row_mask:0xf bank_mask:0xf bound_ctrl:1
	s_nop 1
	v_add_f32_dpp v136, v136, v136 row_shr:2 row_mask:0xf bank_mask:0xf bound_ctrl:1
	s_nop 1
	v_add_f32_dpp v136, v136, v136 row_shr:4 row_mask:0xf bank_mask:0xf bound_ctrl:1
	s_nop 1
	v_add_f32_dpp v136, v136, v136 row_shr:8 row_mask:0xf bank_mask:0xf bound_ctrl:1
	s_nop 0
	v_max_f32_e32 v136, 0xc2a00000, v136
	v_mul_f32_e32 v136, 0x3fb8aa3b, v136
	v_exp_f32_e32 v138, v136
	v_exp_f32_e64 v139, -v136
	s_nop 0
	v_mul_f32_e32 v136, 0x3db504f3, v138
	ds_write_b128 v148, v[120:123]
	ds_write_b128 v148, v[124:127] offset:16
	ds_write_b128 v148, v[128:131] offset:8192
	ds_write_b128 v148, v[132:135] offset:8208
	ds_write_b32 v149, v137
	ds_write_b32 v150, v139 offset:17408
	ds_write_b32 v150, v138 offset:17536
	ds_write_b32 v150, v136 offset:17472
	global_load_dwordx4 v[108:111], v118, s[4:5]
	global_load_dwordx4 v[112:115], v118, s[4:5] offset:1024
	global_load_ushort v116, v119, s[4:5]
	global_load_dword v117, v140, s[6:7]
	s_add_u32 s4, s4, 0xc000
	s_addc_u32 s5, s5, 0
	s_add_u32 s6, s6, 0x200
	s_addc_u32 s7, s7, 0
	s_mov_b32 s0, 0
	s_mov_b32 s1, 0
	s_waitcnt lgkmcnt(0)
	s_barrier
	ds_read_b128 v[20:23], v151 offset:8192
	ds_read_b128 v[28:31], v151 offset:0
	ds_read_b128 v[24:27], v151 offset:8256
	ds_read_b128 v[32:35], v151 offset:64
; __device__ __forceinline__ void gdn_item(const Params& p, int item, float* sm) {
;     ...
;   for (int ch = 0; ch < NCH; ch++) {
;     const int bi = ch & 1;
;     const int t0 = PADR + ch * TC;
;     if (ch + 1 < NCH) GDN_LOAD(t0 + TC)
;     {
;       const float* bq = sm + bi * BUF;
;       const float* bk = bq + TC * 128;
;       const float* bv = bq + 2 * TC * 128;
;       const float* bg = bv + TC * 16;
;       float* bo = sm + bi * BUF + 2 * TC * 128 + TC * 16 + 2 * TC;
;       float oreg[TC];
; #pragma unroll
;       for (int t = 0; t < TC; t++) {
;         const float4 k0 = *(const float4*)(bk + t * 128 + sub * 4);
;         const float4 k1 = *(const float4*)(bk + t * 128 + 64 + sub * 4);
;         const float4 q0 = *(const float4*)(bq + t * 128 + sub * 4);
;         const float4 q1 = *(const float4*)(bq + t * 128 + 64 + sub * 4);
;         const float v = bv[t * 16 + cw];
;         const float g = bg[t], be = bg[TC + t];
;         const float qk = bo[TC * 16 + t];
;         float pa = k0.x * S[0] + k0.y * S[1];
;         float pb2 = k0.z * S[2] + k0.w * S[3];
;         float qa = q0.x * S[0] + q0.y * S[1];
;         float qb2 = q0.z * S[2] + q0.w * S[3];
;         pa += k1.x * S[4] + k1.y * S[5];
;         pb2 += k1.z * S[6] + k1.w * S[7];
;         qa += q1.x * S[4] + q1.y * S[5];
;         qb2 += q1.z * S[6] + q1.w * S[7];
;         const float ks = dpp_sum16(pa + pb2);
;         const float qs = dpp_sum16(qa + qb2);
;         const float coef = be * (v - g * ks);
;         const float oo = g * qs + coef * qk;
;         S[0] = g * S[0] + coef * k0.x; S[1] = g * S[1] + coef * k0.y; S[2] = g * S[2] + coef * k0.z; S[3] = g * S[3] + coef * k0.w;
;         S[4] = g * S[4] + coef * k1.x; S[5] = g * S[5] + coef * k1.y; S[6] = g * S[6] + coef * k1.z; S[7] = g * S[7] + coef * k1.w;
;         oreg[t] = oo * 0.08838834764831845f;
;       }
;       if (sub == 0) {
; #pragma unroll
;         for (int t = 0; t < TC; t++) bo[t * 16 + cw] = oreg[t];
;       }
;     }
;     if (ch + 1 < NCH) GDN_STORE(bi ^ 1)
;     __syncthreads();
;     {
;       const float ov = sm[bi * BUF + 2 * TC * 128 + TC * 16 + 2 * TC + ltt * 16 + lseg];
;       O[(rowb + t0 + ltt) * D + 512 + h * 128 + c0 + lseg] = f2bf(ov);
;     }
.Lgd_chunk:
	v_add_u32_e32 v141, s1, v151
	v_add_u32_e32 v142, s1, v152
	v_add_u32_e32 v143, s1, v153
	v_add_u32_e32 v144, s1, v154
	v_mov_b32_e32 v145, s1
	s_xor_b32 s2, s1, 0x4500
	s_and_b32 s12, s0, 1
	s_mul_i32 s12, s12, 0x3000
	v_add_u32_e32 v146, s12, v155
	v_add_u32_e32 v147, s12, v156
	v_add_u32_e32 v178, s2, v151
	v_add_u32_e32 v148, s2, v157
	v_add_u32_e32 v149, s2, v158
	v_add_u32_e32 v150, s2, v159
	s_waitcnt lgkmcnt(0)
	v_mfma_f32_16x16x4_f32 v[60:63], v20, v12, 0
	ds_read_b32 v36, v142 offset:8192
	v_mfma_f32_16x16x4_f32 v[64:67], v28, v12, 0
	ds_read_b32 v37, v142 offset:8704
	v_mfma_f32_16x16x4_f32 v[60:63], v21, v13, v[60:63]
	ds_read_b32 v38, v142 offset:9216
	v_mfma_f32_16x16x4_f32 v[64:67], v29, v13, v[64:67]
	ds_read_b32 v39, v142 offset:9728
	s_waitcnt vmcnt(0)
	v_lshlrev_b32_e32 v120, 16, v108
	v_and_b32_e32 v121, 0xffff0000, v108
	v_lshlrev_b32_e32 v122, 16, v109
	v_mfma_f32_16x16x4_f32 v[60:63], v22, v14, v[60:63]
	ds_read_b32 v40, v142 offset:8256
	v_and_b32_e32 v123, 0xffff0000, v109
	v_lshlrev_b32_e32 v124, 16, v110
	v_and_b32_e32 v125, 0xffff0000, v110
	v_mfma_f32_16x16x4_f32 v[64:67], v30, v14, v[64:67]
	ds_read_b32 v41, v142 offset:8768
	v_lshlrev_b32_e32 v126, 16, v111
	v_and_b32_e32 v127, 0xffff0000, v111
	v_lshlrev_b32_e32 v128, 16, v112
	v_and_b32_e32 v129, 0xffff0000, v112
	v_mfma_f32_16x16x4_f32 v[60:63], v23, v15, v[60:63]
	ds_read_b32 v42, v142 offset:9280
	v_lshlrev_b32_e32 v130, 16, v113
	v_and_b32_e32 v131, 0xffff0000, v113
	v_lshlrev_b32_e32 v132, 16, v114
	v_mfma_f32_16x16x4_f32 v[64:67], v31, v15, v[64:67]
	ds_read_b32 v43, v142 offset:9792
	v_and_b32_e32 v133, 0xffff0000, v114
	v_lshlrev_b32_e32 v134, 16, v115
	v_and_b32_e32 v135, 0xffff0000, v115
	v_mov_b32_e32 v136, v117
	v_mfma_f32_16x16x4_f32 v[60:63], v24, v16, v[60:63]
	ds_read_b128 v[44:47], v143 offset:16384
	v_lshlrev_b32_e32 v137, 16, v116
	s_nop 0
	v_add_f32_dpp v136, v136, v136 row_shr:1 row_mask:0xf bank_mask:0xf bound_ctrl:1
	v_mfma_f32_16x16x4_f32 v[64:67], v32, v16, v[64:67]
	ds_read_b128 v[48:51], v144 offset:17408
	s_nop 1
	v_add_f32_dpp v136, v136, v136 row_shr:2 row_mask:0xf bank_mask:0xf bound_ctrl:1
	s_nop 1
	v_add_f32_dpp v136, v136, v136 row_shr:4 row_mask:0xf bank_mask:0xf bound_ctrl:1
	v_mfma_f32_16x16x4_f32 v[60:63], v25, v17, v[60:63]
	ds_read_b128 v[52:55], v144 offset:17472
	s_nop 1
	v_add_f32_dpp v136, v136, v136 row_shr:8 row_mask:0xf bank_mask:0xf bound_ctrl:1
	s_nop 0
	v_mfma_f32_16x16x4_f32 v[64:67], v33, v17, v[64:67]
	ds_read_b32 v56, v145 offset:17596
	v_max_f32_e32 v136, 0xc2a00000, v136
	v_mul_f32_e32 v136, 0x3fb8aa3b, v136
	v_exp_f32_e32 v138, v136
	v_exp_f32_e64 v139, -v136
	v_mfma_f32_16x16x4_f32 v[60:63], v26, v18, v[60:63]
	s_nop 0
	v_mul_f32_e32 v136, 0x3db504f3, v138
	ds_write_b128 v148, v[120:123]
	v_mfma_f32_16x16x4_f32 v[64:67], v34, v18, v[64:67]
	ds_write_b128 v148, v[124:127] offset:16
	ds_write_b128 v148, v[128:131] offset:8192
	ds_write_b128 v148, v[132:135] offset:8208
	ds_write_b32 v149, v137
	v_mfma_f32_16x16x4_f32 v[60:63], v27, v19, v[60:63]
	ds_write_b32 v150, v139 offset:17408
	ds_write_b32 v150, v138 offset:17536
	ds_write_b32 v150, v136 offset:17472
	v_mfma_f32_16x16x4_f32 v[64:67], v35, v19, v[64:67]
	global_load_dwordx4 v[108:111], v118, s[4:5]
	global_load_dwordx4 v[112:115], v118, s[4:5] offset:1024
	global_load_ushort v116, v119, s[4:5]
	global_load_dword v117, v140, s[6:7]
	s_cmp_lt_u32 s0, 0x1fe
	s_cselect_b32 s12, 0xc000, 0
	s_cselect_b32 s101, 0x200, 0
	s_add_u32 s4, s4, s12
	s_addc_u32 s5, s5, 0
	s_add_u32 s6, s6, s101
	s_addc_u32 s7, s7, 0
	s_nop 3
	ds_write_b128 v146, v[60:63]
	ds_write_b128 v146, v[64:67] offset:1024
	s_waitcnt lgkmcnt(0)
	s_barrier
	ds_read_b128 v[72:75], v147 offset:0
	ds_read_b128 v[76:79], v147 offset:3072
	ds_read_b128 v[80:83], v147 offset:6144
	ds_read_b128 v[84:87], v147 offset:9216
	s_waitcnt lgkmcnt(0)
	v_add_f32_e32 v72, v72, v76
	v_add_f32_e32 v80, v80, v84
	v_add_f32_e32 v73, v73, v77
	v_add_f32_e32 v81, v81, v85
	v_add_f32_e32 v74, v74, v78
	v_add_f32_e32 v82, v82, v86
	v_add_f32_e32 v75, v75, v79
	v_add_f32_e32 v83, v83, v87
	v_add_f32_e32 v72, v72, v80
	v_add_f32_e32 v73, v73, v81
	v_add_f32_e32 v74, v74, v82
	v_add_f32_e32 v75, v75, v83
	v_fma_f32 v96, v44, v48, -v72
	v_fma_f32 v97, v45, v49, -v73
	v_fma_f32 v98, v46, v50, -v74
	v_fma_f32 v99, v47, v51, -v75
	s_nop 1
	v_mfma_f32_16x16x4_f32 v[100:103], v88, v96, 0
	v_mfma_f32_16x16x4_f32 v[100:103], v89, v97, v[100:103]
	v_mfma_f32_16x16x4_f32 v[100:103], v90, v98, v[100:103]
	v_mfma_f32_16x16x4_f32 v[100:103], v91, v99, v[100:103]
	global_load_dwordx4 v[88:91], v59, s[10:11]
	s_cmp_lt_u32 s0, 0x1ff
	s_cselect_b32 s12, 0x400, 0
	s_add_u32 s10, s10, s12
	s_addc_u32 s11, s11, 0
	ds_read_b128 v[20:23], v178 offset:8192
	ds_read_b128 v[28:31], v178 offset:0
	ds_read_b128 v[24:27], v178 offset:8256
	ds_read_b128 v[32:35], v178 offset:64
	s_and_b32 s12, s0, 3
	s_cmp_eq_u32 s12, s100
	s_cbranch_scc0 .Lgd_upd
	ds_read_b128 v[72:75], v147 offset:1024
	ds_read_b128 v[76:79], v147 offset:4096
	ds_read_b128 v[80:83], v147 offset:7168
	ds_read_b128 v[84:87], v147 offset:10240
	s_waitcnt lgkmcnt(0)
	v_add_f32_e32 v72, v72, v76
	v_add_f32_e32 v80, v80, v84
	v_add_f32_e32 v73, v73, v77
	v_add_f32_e32 v81, v81, v85
	v_add_f32_e32 v74, v74, v78
	v_add_f32_e32 v82, v82, v86
	v_add_f32_e32 v75, v75, v79
	v_add_f32_e32 v83, v83, v87
	v_add_f32_e32 v104, v72, v80
	v_add_f32_e32 v105, v73, v81
	v_add_f32_e32 v106, v74, v82
	v_add_f32_e32 v107, v75, v83
	s_nop 7
	s_nop 1
	v_mfma_f32_16x16x4_f32 v[104:107], v92, v100, v[104:107]
	v_mfma_f32_16x16x4_f32 v[104:107], v93, v101, v[104:107]
	v_mfma_f32_16x16x4_f32 v[104:107], v94, v102, v[104:107]
	v_mfma_f32_16x16x4_f32 v[104:107], v95, v103, v[104:107]
